# stagger non-tail workgroups in residual GEMM phases; SwiGLU epilogue vmcnt(0)->vmcnt(8)
# baseline (speedup 1.0000x reference)
; __device__ __forceinline__ unsigned cvt_pk_bf16(float lo, float hi) { unsigned r; asm volatile("v_cvt_pk_bf16_f32 %0, %1, %2" : "=v"(r) : "v"(lo), "v"(hi)); return r; }
; __device__ __forceinline__ f32x2 swiglu_pk(f32x2 g, f32x2 u) {
;     const f32x2 t = g * (-1.4426950408889634f); f32x2 e; e.x = __builtin_amdgcn_exp2f(t.x); e.y = __builtin_amdgcn_exp2f(t.y);
;     const f32x2 d = e + 1.0f; f32x2 r; r.x = __builtin_amdgcn_rcpf(d.x); r.y = __builtin_amdgcn_rcpf(d.y);
;     return (g * u) * r; }
;     __device__ __forceinline__ void operator()(const f32x4 (&acc)[2][2][4][2], const Unit& u, int wr, int wc, int fr, int fq, const Pf& pf) const {
;         const int row0 = u.pm * BM + wr * 64 + fr, col0 = u.pn * HALF + wc * 32 + 8 * fq;
;         const f32x4 bg0 = pf.bg0, bg1 = pf.bg1, bu0 = pf.bu0, bu1 = pf.bu1;
; #pragma unroll
;         for (int ai = 0; ai < 2; ++ai)
; #pragma unroll
;             for (int m = 0; m < 4; ++m) { const int row = row0 + ai * HALF + m * 16; bf16_t* rowp = O + (size_t)row * ldc + col0; const float rs = __builtin_amdgcn_rsqf(pf.r[ai][m] * (1.0f / 1024.0f) + 1e-6f);
;                 const f32x4 g0 = acc[ai][0][m][0] * rs + bg0, g1 = acc[ai][0][m][1] * rs + bg1, u0 = acc[ai][1][m][0] * rs + bu0, u1 = acc[ai][1][m][1] * rs + bu1;
;                 const f32x2 ha = swiglu_pk((f32x2){g0[0], g0[1]}, (f32x2){u0[0], u0[1]}), hb = swiglu_pk((f32x2){g0[2], g0[3]}, (f32x2){u0[2], u0[3]});
;                 const f32x2 hc = swiglu_pk((f32x2){g1[0], g1[1]}, (f32x2){u1[0], u1[1]}), hd = swiglu_pk((f32x2){g1[2], g1[3]}, (f32x2){u1[2], u1[3]});
;                 u32x4 w; w.x = cvt_pk_bf16(ha.x, ha.y); w.y = cvt_pk_bf16(hb.x, hb.y); w.z = cvt_pk_bf16(hc.x, hc.y); w.w = cvt_pk_bf16(hd.x, hd.y);
;                 *(u32x4*)rowp = w; }
.LBB0_272:
	s_waitcnt vmcnt(8)
	v_fmamk_f32 v172, v172, 0x3a800000, v238
	v_rsq_f32_e32 v172, v172
	v_add_u32_e32 v173, 0x80, v156
	v_lshl_or_b32 v160, s12, 7, v164
	v_ashrrev_i32_e32 v161, 31, v160
	v_pk_fma_f32 v[144:145], v[172:173], v[144:145], v[10:11] op_sel_hi:[0,1,1]
	v_pk_fma_f32 v[142:143], v[172:173], v[142:143], v[8:9] op_sel_hi:[0,1,1]
	v_pk_fma_f32 v[134:135], v[172:173], v[134:135], v[12:13] op_sel_hi:[0,1,1]
	v_pk_mul_f32 v[176:177], v[142:143], s[34:35] op_sel_hi:[1,0]
	v_pk_mul_f32 v[134:135], v[134:135], v[142:143]
	v_pk_mul_f32 v[142:143], v[144:145], s[34:35] op_sel_hi:[1,0]
	v_pk_fma_f32 v[136:137], v[172:173], v[136:137], v[14:15] op_sel_hi:[0,1,1]
	v_exp_f32_e32 v142, v142
	v_exp_f32_e32 v143, v143
	v_pk_fma_f32 v[138:139], v[172:173], v[138:139], v[0:1] op_sel_hi:[0,1,1]
	v_pk_mul_f32 v[136:137], v[136:137], v[144:145]
	v_pk_fma_f32 v[130:131], v[172:173], v[130:131], v[4:5] op_sel_hi:[0,1,1]
	v_pk_add_f32 v[142:143], v[142:143], 1.0 op_sel_hi:[1,0]
	v_pk_fma_f32 v[140:141], v[172:173], v[140:141], v[2:3] op_sel_hi:[0,1,1]
	v_rcp_f32_e32 v142, v142
	v_rcp_f32_e32 v143, v143
	v_pk_mul_f32 v[130:131], v[130:131], v[138:139]
	v_exp_f32_e32 v176, v176
	v_exp_f32_e32 v177, v177
	v_pk_mul_f32 v[136:137], v[136:137], v[142:143]
	v_pk_mul_f32 v[142:143], v[138:139], s[34:35] op_sel_hi:[1,0]
	v_mov_b64_e32 v[158:159], s[18:19]
	v_exp_f32_e32 v142, v142
	v_exp_f32_e32 v143, v143
	v_pk_add_f32 v[176:177], v[176:177], 1.0 op_sel_hi:[1,0]
	s_movk_i32 s12, 0x1600
	v_rcp_f32_e32 v176, v176
	v_pk_add_f32 v[142:143], v[142:143], 1.0 op_sel_hi:[1,0]
	v_rcp_f32_e32 v177, v177
	v_rcp_f32_e32 v142, v142
	v_rcp_f32_e32 v143, v143
	v_pk_fma_f32 v[132:133], v[172:173], v[132:133], v[6:7] op_sel_hi:[0,1,1]
	v_mad_i64_i32 v[174:175], s[38:39], v156, s12, v[158:159]
	v_pk_mul_f32 v[138:139], v[130:131], v[142:143]
	v_pk_mul_f32 v[130:131], v[140:141], s[34:35] op_sel_hi:[1,0]
	v_lshlrev_b64 v[160:161], 1, v[160:161]
	v_exp_f32_e32 v130, v130
	v_exp_f32_e32 v131, v131
	v_pk_mul_f32 v[132:133], v[132:133], v[140:141]
	v_lshl_add_u64 v[174:175], v[174:175], 0, v[160:161]
	v_pk_mul_f32 v[134:135], v[134:135], v[176:177]
	v_pk_add_f32 v[130:131], v[130:131], 1.0 op_sel_hi:[1,0]
	v_readlane_b32 s54, v254, 37
	v_rcp_f32_e32 v130, v130
	v_rcp_f32_e32 v131, v131
	s_mov_b64 s[52:53], -1
	s_andn2_b64 vcc, exec, s[4:5]
	v_readlane_b32 s55, v254, 38
	v_pk_mul_f32 v[140:141], v[132:133], v[130:131]
	v_cvt_pk_bf16_f32 v130, v134, v135
	v_cvt_pk_bf16_f32 v131, v136, v137
	v_cvt_pk_bf16_f32 v132, v138, v139
	v_mov_b32_e32 v247, v239
	v_cvt_pk_bf16_f32 v133, v140, v141
	global_store_dwordx4 v[174:175], v[130:133], off
	s_nop 1
	v_fmamk_f32 v132, v171, 0x3a800000, v238
	v_rsq_f32_e32 v132, v132
	v_or_b32_e32 v130, 16, v156
	v_mad_i64_i32 v[130:131], s[38:39], v130, s12, v[158:159]
	v_pk_fma_f32 v[126:127], v[132:133], v[126:127], v[10:11] op_sel_hi:[0,1,1]
	v_pk_fma_f32 v[124:125], v[132:133], v[124:125], v[8:9] op_sel_hi:[0,1,1]
	v_pk_fma_f32 v[116:117], v[132:133], v[116:117], v[12:13] op_sel_hi:[0,1,1]
	v_pk_fma_f32 v[122:123], v[132:133], v[122:123], v[2:3] op_sel_hi:[0,1,1]
	v_pk_fma_f32 v[120:121], v[132:133], v[120:121], v[0:1] op_sel_hi:[0,1,1]
	v_pk_fma_f32 v[118:119], v[132:133], v[118:119], v[14:15] op_sel_hi:[0,1,1]
	v_pk_fma_f32 v[112:113], v[132:133], v[112:113], v[4:5] op_sel_hi:[0,1,1]
	v_pk_fma_f32 v[114:115], v[132:133], v[114:115], v[6:7] op_sel_hi:[0,1,1]
	v_pk_mul_f32 v[132:133], v[124:125], s[34:35] op_sel_hi:[1,0]
	v_pk_mul_f32 v[116:117], v[116:117], v[124:125]
	v_pk_mul_f32 v[124:125], v[126:127], s[34:35] op_sel_hi:[1,0]
	v_pk_mul_f32 v[118:119], v[118:119], v[126:127]
	v_exp_f32_e32 v124, v124
	v_exp_f32_e32 v125, v125
	v_pk_mul_f32 v[112:113], v[112:113], v[120:121]
	v_exp_f32_e32 v132, v132
	v_exp_f32_e32 v133, v133
	v_pk_add_f32 v[124:125], v[124:125], 1.0 op_sel_hi:[1,0]
	v_pk_mul_f32 v[114:115], v[114:115], v[122:123]
	v_rcp_f32_e32 v124, v124
	v_rcp_f32_e32 v125, v125
	v_pk_add_f32 v[132:133], v[132:133], 1.0 op_sel_hi:[1,0]
	v_lshl_add_u64 v[130:131], v[130:131], 0, v[160:161]
	v_rcp_f32_e32 v132, v132
	v_pk_mul_f32 v[118:119], v[118:119], v[124:125]
	v_pk_mul_f32 v[124:125], v[120:121], s[34:35] op_sel_hi:[1,0]
	v_rcp_f32_e32 v133, v133
	v_exp_f32_e32 v124, v124
	v_exp_f32_e32 v125, v125
	v_pk_mul_f32 v[116:117], v[116:117], v[132:133]
	v_pk_add_f32 v[124:125], v[124:125], 1.0 op_sel_hi:[1,0]
	s_nop 0
	v_rcp_f32_e32 v124, v124
	v_rcp_f32_e32 v125, v125
	s_nop 0
	v_pk_mul_f32 v[120:121], v[112:113], v[124:125]
	v_pk_mul_f32 v[112:113], v[122:123], s[34:35] op_sel_hi:[1,0]
	s_nop 0
	v_exp_f32_e32 v112, v112
	v_exp_f32_e32 v113, v113
	s_nop 0
	v_pk_add_f32 v[112:113], v[112:113], 1.0 op_sel_hi:[1,0]
	s_nop 0
	v_rcp_f32_e32 v112, v112
	v_rcp_f32_e32 v113, v113
	s_nop 0
	v_pk_mul_f32 v[122:123], v[114:115], v[112:113]
	v_cvt_pk_bf16_f32 v112, v116, v117
	v_cvt_pk_bf16_f32 v113, v118, v119
	v_cvt_pk_bf16_f32 v114, v120, v121
	s_nop 0
	v_cvt_pk_bf16_f32 v115, v122, v123
	global_store_dwordx4 v[130:131], v[112:115], off
	s_nop 1
	v_fmamk_f32 v114, v170, 0x3a800000, v238
	v_rsq_f32_e32 v114, v114
	v_or_b32_e32 v112, 32, v156
	v_mad_i64_i32 v[112:113], s[38:39], v112, s12, v[158:159]
	v_pk_fma_f32 v[110:111], v[114:115], v[110:111], v[10:11] op_sel_hi:[0,1,1]
	v_pk_fma_f32 v[108:109], v[114:115], v[108:109], v[8:9] op_sel_hi:[0,1,1]
	v_pk_fma_f32 v[100:101], v[114:115], v[100:101], v[12:13] op_sel_hi:[0,1,1]
	v_pk_fma_f32 v[106:107], v[114:115], v[106:107], v[2:3] op_sel_hi:[0,1,1]
	v_pk_fma_f32 v[104:105], v[114:115], v[104:105], v[0:1] op_sel_hi:[0,1,1]
	v_pk_fma_f32 v[102:103], v[114:115], v[102:103], v[14:15] op_sel_hi:[0,1,1]
; __device__ __forceinline__ unsigned cvt_pk_bf16(float lo, float hi) { unsigned r; asm volatile("v_cvt_pk_bf16_f32 %0, %1, %2" : "=v"(r) : "v"(lo), "v"(hi)); return r; }
; __device__ __forceinline__ f32x2 swiglu_pk(f32x2 g, f32x2 u) {
;     const f32x2 t = g * (-1.4426950408889634f); f32x2 e; e.x = __builtin_amdgcn_exp2f(t.x); e.y = __builtin_amdgcn_exp2f(t.y);
;     const f32x2 d = e + 1.0f; f32x2 r; r.x = __builtin_amdgcn_rcpf(d.x); r.y = __builtin_amdgcn_rcpf(d.y);
;     return (g * u) * r; }
;     __device__ __forceinline__ void operator()(const f32x4 (&acc)[2][2][4][2], const Unit& u, int wr, int wc, int fr, int fq, const Pf& pf) const {
;     ...
;             for (int m = 0; m < 4; ++m) { const int row = row0 + ai * HALF + m * 16; bf16_t* rowp = O + (size_t)row * ldc + col0; const float rs = __builtin_amdgcn_rsqf(pf.r[ai][m] * (1.0f / 1024.0f) + 1e-6f);
;                 const f32x4 g0 = acc[ai][0][m][0] * rs + bg0, g1 = acc[ai][0][m][1] * rs + bg1, u0 = acc[ai][1][m][0] * rs + bu0, u1 = acc[ai][1][m][1] * rs + bu1;
;                 const f32x2 ha = swiglu_pk((f32x2){g0[0], g0[1]}, (f32x2){u0[0], u0[1]}), hb = swiglu_pk((f32x2){g0[2], g0[3]}, (f32x2){u0[2], u0[3]});
;                 const f32x2 hc = swiglu_pk((f32x2){g1[0], g1[1]}, (f32x2){u1[0], u1[1]}), hd = swiglu_pk((f32x2){g1[2], g1[3]}, (f32x2){u1[2], u1[3]});
;                 u32x4 w; w.x = cvt_pk_bf16(ha.x, ha.y); w.y = cvt_pk_bf16(hb.x, hb.y); w.z = cvt_pk_bf16(hc.x, hc.y); w.w = cvt_pk_bf16(hd.x, hd.y);
;                 *(u32x4*)rowp = w; }
	v_pk_fma_f32 v[96:97], v[114:115], v[96:97], v[4:5] op_sel_hi:[0,1,1]
	v_pk_fma_f32 v[98:99], v[114:115], v[98:99], v[6:7] op_sel_hi:[0,1,1]
	v_pk_mul_f32 v[114:115], v[108:109], s[34:35] op_sel_hi:[1,0]
	v_pk_mul_f32 v[100:101], v[100:101], v[108:109]
	v_pk_mul_f32 v[108:109], v[110:111], s[34:35] op_sel_hi:[1,0]
	v_pk_mul_f32 v[102:103], v[102:103], v[110:111]
	v_exp_f32_e32 v108, v108
	v_exp_f32_e32 v109, v109
	v_pk_mul_f32 v[96:97], v[96:97], v[104:105]
	v_exp_f32_e32 v114, v114
	v_exp_f32_e32 v115, v115
	v_pk_add_f32 v[108:109], v[108:109], 1.0 op_sel_hi:[1,0]
	v_pk_mul_f32 v[98:99], v[98:99], v[106:107]
	v_rcp_f32_e32 v108, v108
	v_rcp_f32_e32 v109, v109
	v_pk_add_f32 v[114:115], v[114:115], 1.0 op_sel_hi:[1,0]
	v_lshl_add_u64 v[112:113], v[112:113], 0, v[160:161]
	v_rcp_f32_e32 v114, v114
	v_pk_mul_f32 v[102:103], v[102:103], v[108:109]
	v_pk_mul_f32 v[108:109], v[104:105], s[34:35] op_sel_hi:[1,0]
	v_rcp_f32_e32 v115, v115
	v_exp_f32_e32 v108, v108
	v_exp_f32_e32 v109, v109
	v_pk_mul_f32 v[100:101], v[100:101], v[114:115]
	v_pk_add_f32 v[108:109], v[108:109], 1.0 op_sel_hi:[1,0]
	s_nop 0
	v_rcp_f32_e32 v108, v108
	v_rcp_f32_e32 v109, v109
	s_nop 0
	v_pk_mul_f32 v[104:105], v[96:97], v[108:109]
	v_pk_mul_f32 v[96:97], v[106:107], s[34:35] op_sel_hi:[1,0]
	s_nop 0
	v_exp_f32_e32 v96, v96
	v_exp_f32_e32 v97, v97
	s_nop 0
	v_pk_add_f32 v[96:97], v[96:97], 1.0 op_sel_hi:[1,0]
	s_nop 0
	v_rcp_f32_e32 v96, v96
	v_rcp_f32_e32 v97, v97
	s_nop 0
	v_pk_mul_f32 v[106:107], v[98:99], v[96:97]
	v_cvt_pk_bf16_f32 v96, v100, v101
	v_cvt_pk_bf16_f32 v97, v102, v103
	v_cvt_pk_bf16_f32 v98, v104, v105
	s_nop 0
	v_cvt_pk_bf16_f32 v99, v106, v107
	global_store_dwordx4 v[112:113], v[96:99], off
	s_nop 1
	v_fmamk_f32 v98, v169, 0x3a800000, v238
	v_rsq_f32_e32 v98, v98
	v_or_b32_e32 v96, 48, v156
	v_mad_i64_i32 v[96:97], s[38:39], v96, s12, v[158:159]
	v_pk_fma_f32 v[94:95], v[98:99], v[94:95], v[10:11] op_sel_hi:[0,1,1]
	v_pk_fma_f32 v[92:93], v[98:99], v[92:93], v[8:9] op_sel_hi:[0,1,1]
	v_pk_fma_f32 v[84:85], v[98:99], v[84:85], v[12:13] op_sel_hi:[0,1,1]
	v_pk_fma_f32 v[90:91], v[98:99], v[90:91], v[2:3] op_sel_hi:[0,1,1]
	v_pk_fma_f32 v[88:89], v[98:99], v[88:89], v[0:1] op_sel_hi:[0,1,1]
	v_pk_fma_f32 v[86:87], v[98:99], v[86:87], v[14:15] op_sel_hi:[0,1,1]
	v_pk_fma_f32 v[80:81], v[98:99], v[80:81], v[4:5] op_sel_hi:[0,1,1]
	v_pk_fma_f32 v[82:83], v[98:99], v[82:83], v[6:7] op_sel_hi:[0,1,1]
	v_pk_mul_f32 v[98:99], v[92:93], s[34:35] op_sel_hi:[1,0]
	v_pk_mul_f32 v[84:85], v[84:85], v[92:93]
	v_pk_mul_f32 v[92:93], v[94:95], s[34:35] op_sel_hi:[1,0]
	v_pk_mul_f32 v[86:87], v[86:87], v[94:95]
	v_exp_f32_e32 v92, v92
	v_exp_f32_e32 v93, v93
	v_pk_mul_f32 v[80:81], v[80:81], v[88:89]
	v_exp_f32_e32 v98, v98
	v_exp_f32_e32 v99, v99
	v_pk_add_f32 v[92:93], v[92:93], 1.0 op_sel_hi:[1,0]
	v_pk_mul_f32 v[82:83], v[82:83], v[90:91]
	v_rcp_f32_e32 v92, v92
	v_rcp_f32_e32 v93, v93
	v_pk_add_f32 v[98:99], v[98:99], 1.0 op_sel_hi:[1,0]
	v_lshl_add_u64 v[96:97], v[96:97], 0, v[160:161]
	v_rcp_f32_e32 v98, v98
	v_pk_mul_f32 v[86:87], v[86:87], v[92:93]
	v_pk_mul_f32 v[92:93], v[88:89], s[34:35] op_sel_hi:[1,0]
	v_rcp_f32_e32 v99, v99
	v_exp_f32_e32 v92, v92
	v_exp_f32_e32 v93, v93
	v_pk_mul_f32 v[84:85], v[84:85], v[98:99]
	v_pk_add_f32 v[92:93], v[92:93], 1.0 op_sel_hi:[1,0]
	s_nop 0
	v_rcp_f32_e32 v92, v92
	v_rcp_f32_e32 v93, v93
	s_nop 0
	v_pk_mul_f32 v[88:89], v[80:81], v[92:93]
	v_pk_mul_f32 v[80:81], v[90:91], s[34:35] op_sel_hi:[1,0]
	s_nop 0
	v_exp_f32_e32 v80, v80
	v_exp_f32_e32 v81, v81
	s_nop 0
	v_pk_add_f32 v[80:81], v[80:81], 1.0 op_sel_hi:[1,0]
	s_nop 0
	v_rcp_f32_e32 v80, v80
	v_rcp_f32_e32 v81, v81
	s_nop 0
	v_pk_mul_f32 v[90:91], v[82:83], v[80:81]
	v_cvt_pk_bf16_f32 v80, v84, v85
	v_cvt_pk_bf16_f32 v81, v86, v87
	v_cvt_pk_bf16_f32 v82, v88, v89
	s_nop 0
	v_cvt_pk_bf16_f32 v83, v90, v91
	global_store_dwordx4 v[96:97], v[80:83], off
	s_nop 1
	v_fmamk_f32 v82, v168, 0x3a800000, v238
	v_rsq_f32_e32 v82, v82
	v_mad_i64_i32 v[80:81], s[38:39], v173, s12, v[158:159]
	v_lshl_add_u64 v[80:81], v[80:81], 0, v[160:161]
	v_pk_fma_f32 v[78:79], v[82:83], v[78:79], v[10:11] op_sel_hi:[0,1,1]
	v_pk_fma_f32 v[76:77], v[82:83], v[76:77], v[8:9] op_sel_hi:[0,1,1]
	v_pk_fma_f32 v[68:69], v[82:83], v[68:69], v[12:13] op_sel_hi:[0,1,1]
	v_pk_fma_f32 v[74:75], v[82:83], v[74:75], v[2:3] op_sel_hi:[0,1,1]
	v_pk_fma_f32 v[72:73], v[82:83], v[72:73], v[0:1] op_sel_hi:[0,1,1]
	v_pk_fma_f32 v[70:71], v[82:83], v[70:71], v[14:15] op_sel_hi:[0,1,1]
	v_pk_fma_f32 v[64:65], v[82:83], v[64:65], v[4:5] op_sel_hi:[0,1,1]
	v_pk_fma_f32 v[66:67], v[82:83], v[66:67], v[6:7] op_sel_hi:[0,1,1]
	v_pk_mul_f32 v[82:83], v[76:77], s[34:35] op_sel_hi:[1,0]
	v_pk_mul_f32 v[68:69], v[68:69], v[76:77]
	v_pk_mul_f32 v[76:77], v[78:79], s[34:35] op_sel_hi:[1,0]
	v_pk_mul_f32 v[70:71], v[70:71], v[78:79]
	v_exp_f32_e32 v76, v76
	v_exp_f32_e32 v77, v77
	v_pk_mul_f32 v[64:65], v[64:65], v[72:73]
	v_exp_f32_e32 v82, v82
	v_exp_f32_e32 v83, v83
	v_pk_add_f32 v[76:77], v[76:77], 1.0 op_sel_hi:[1,0]
	v_pk_mul_f32 v[66:67], v[66:67], v[74:75]
	v_rcp_f32_e32 v76, v76
	v_rcp_f32_e32 v77, v77
	v_pk_add_f32 v[82:83], v[82:83], 1.0 op_sel_hi:[1,0]
	v_pk_mul_f32 v[70:71], v[70:71], v[76:77]
	v_pk_mul_f32 v[76:77], v[72:73], s[34:35] op_sel_hi:[1,0]
	v_rcp_f32_e32 v82, v82
	v_exp_f32_e32 v76, v76
	v_exp_f32_e32 v77, v77
	v_rcp_f32_e32 v83, v83
	v_pk_add_f32 v[76:77], v[76:77], 1.0 op_sel_hi:[1,0]
	s_nop 0
	v_rcp_f32_e32 v76, v76
	v_rcp_f32_e32 v77, v77
	v_pk_mul_f32 v[68:69], v[68:69], v[82:83]
	v_pk_mul_f32 v[72:73], v[64:65], v[76:77]
	v_pk_mul_f32 v[64:65], v[74:75], s[34:35] op_sel_hi:[1,0]
	s_nop 0
; __device__ __forceinline__ unsigned cvt_pk_bf16(float lo, float hi) { unsigned r; asm volatile("v_cvt_pk_bf16_f32 %0, %1, %2" : "=v"(r) : "v"(lo), "v"(hi)); return r; }
; #define PG8_BAR __builtin_amdgcn_s_barrier()
;     __device__ __forceinline__ void operator()(const f32x4 (&acc)[2][2][4][2], const Unit& u, int wr, int wc, int fr, int fq, const Pf& pf) const {
;     ...
;             for (int m = 0; m < 4; ++m) { const int row = row0 + ai * HALF + m * 16; bf16_t* rowp = O + (size_t)row * ldc + col0; const float rs = __builtin_amdgcn_rsqf(pf.r[ai][m] * (1.0f / 1024.0f) + 1e-6f);
;                 const f32x4 g0 = acc[ai][0][m][0] * rs + bg0, g1 = acc[ai][0][m][1] * rs + bg1, u0 = acc[ai][1][m][0] * rs + bu0, u1 = acc[ai][1][m][1] * rs + bu1;
;                 const f32x2 ha = swiglu_pk((f32x2){g0[0], g0[1]}, (f32x2){u0[0], u0[1]}), hb = swiglu_pk((f32x2){g0[2], g0[3]}, (f32x2){u0[2], u0[3]});
;                 const f32x2 hc = swiglu_pk((f32x2){g1[0], g1[1]}, (f32x2){u1[0], u1[1]}), hd = swiglu_pk((f32x2){g1[2], g1[3]}, (f32x2){u1[2], u1[3]});
;                 u32x4 w; w.x = cvt_pk_bf16(ha.x, ha.y); w.y = cvt_pk_bf16(hb.x, hb.y); w.z = cvt_pk_bf16(hc.x, hc.y); w.w = cvt_pk_bf16(hd.x, hd.y);
;                 *(u32x4*)rowp = w; }
; template <class Epi, class Sched, bool ALIGN_EPI = false, bool SP2 = false>
; __device__ __forceinline__ void gemm_phase(PG8_LAS unsigned char* lds, const Gemm g, const Sched& S, const Epi& E) {
;     ...
;         cur = nxt; cA = nA; cB = nB; ++ui;
;         if constexpr (ALIGN_EPI) { if (wr == 1) PG8_BAR; }
	v_exp_f32_e32 v64, v64
	v_exp_f32_e32 v65, v65
	s_nop 0
	v_pk_add_f32 v[64:65], v[64:65], 1.0 op_sel_hi:[1,0]
	s_nop 0
	v_rcp_f32_e32 v64, v64
	v_rcp_f32_e32 v65, v65
	s_nop 0
	v_pk_mul_f32 v[74:75], v[66:67], v[64:65]
	v_cvt_pk_bf16_f32 v64, v68, v69
	v_cvt_pk_bf16_f32 v65, v70, v71
	v_cvt_pk_bf16_f32 v66, v72, v73
	s_nop 0
	v_cvt_pk_bf16_f32 v67, v74, v75
	global_store_dwordx4 v[80:81], v[64:67], off
	s_nop 1
	v_fmamk_f32 v66, v167, 0x3a800000, v238
	v_rsq_f32_e32 v66, v66
	v_add_u32_e32 v64, 0x90, v156
	v_mad_i64_i32 v[64:65], s[38:39], v64, s12, v[158:159]
	v_pk_fma_f32 v[62:63], v[66:67], v[62:63], v[10:11] op_sel_hi:[0,1,1]
	v_pk_fma_f32 v[60:61], v[66:67], v[60:61], v[8:9] op_sel_hi:[0,1,1]
	v_pk_fma_f32 v[52:53], v[66:67], v[52:53], v[12:13] op_sel_hi:[0,1,1]
	v_pk_fma_f32 v[58:59], v[66:67], v[58:59], v[2:3] op_sel_hi:[0,1,1]
	v_pk_fma_f32 v[56:57], v[66:67], v[56:57], v[0:1] op_sel_hi:[0,1,1]
	v_pk_fma_f32 v[54:55], v[66:67], v[54:55], v[14:15] op_sel_hi:[0,1,1]
	v_pk_fma_f32 v[48:49], v[66:67], v[48:49], v[4:5] op_sel_hi:[0,1,1]
	v_pk_fma_f32 v[50:51], v[66:67], v[50:51], v[6:7] op_sel_hi:[0,1,1]
	v_pk_mul_f32 v[66:67], v[60:61], s[34:35] op_sel_hi:[1,0]
	v_pk_mul_f32 v[52:53], v[52:53], v[60:61]
	v_pk_mul_f32 v[60:61], v[62:63], s[34:35] op_sel_hi:[1,0]
	v_pk_mul_f32 v[54:55], v[54:55], v[62:63]
	v_exp_f32_e32 v60, v60
	v_exp_f32_e32 v61, v61
	v_pk_mul_f32 v[48:49], v[48:49], v[56:57]
	v_exp_f32_e32 v66, v66
	v_exp_f32_e32 v67, v67
	v_pk_add_f32 v[60:61], v[60:61], 1.0 op_sel_hi:[1,0]
	v_pk_mul_f32 v[50:51], v[50:51], v[58:59]
	v_rcp_f32_e32 v60, v60
	v_rcp_f32_e32 v61, v61
	v_pk_add_f32 v[66:67], v[66:67], 1.0 op_sel_hi:[1,0]
	v_lshl_add_u64 v[64:65], v[64:65], 0, v[160:161]
	v_rcp_f32_e32 v66, v66
	v_pk_mul_f32 v[54:55], v[54:55], v[60:61]
	v_pk_mul_f32 v[60:61], v[56:57], s[34:35] op_sel_hi:[1,0]
	v_rcp_f32_e32 v67, v67
	v_exp_f32_e32 v60, v60
	v_exp_f32_e32 v61, v61
	v_pk_mul_f32 v[52:53], v[52:53], v[66:67]
	v_pk_add_f32 v[60:61], v[60:61], 1.0 op_sel_hi:[1,0]
	s_nop 0
	v_rcp_f32_e32 v60, v60
	v_rcp_f32_e32 v61, v61
	s_nop 0
	v_pk_mul_f32 v[56:57], v[48:49], v[60:61]
	v_pk_mul_f32 v[48:49], v[58:59], s[34:35] op_sel_hi:[1,0]
	s_nop 0
	v_exp_f32_e32 v48, v48
	v_exp_f32_e32 v49, v49
	s_nop 0
	v_pk_add_f32 v[48:49], v[48:49], 1.0 op_sel_hi:[1,0]
	s_nop 0
	v_rcp_f32_e32 v48, v48
	v_rcp_f32_e32 v49, v49
	s_nop 0
	v_pk_mul_f32 v[58:59], v[50:51], v[48:49]
	v_cvt_pk_bf16_f32 v48, v52, v53
	v_cvt_pk_bf16_f32 v49, v54, v55
	v_cvt_pk_bf16_f32 v50, v56, v57
	s_nop 0
	v_cvt_pk_bf16_f32 v51, v58, v59
	global_store_dwordx4 v[64:65], v[48:51], off
	s_nop 1
	v_fmamk_f32 v50, v166, 0x3a800000, v238
	v_rsq_f32_e32 v50, v50
	v_add_u32_e32 v48, 0xa0, v156
	v_mad_i64_i32 v[48:49], s[38:39], v48, s12, v[158:159]
	v_pk_fma_f32 v[46:47], v[50:51], v[46:47], v[10:11] op_sel_hi:[0,1,1]
	v_pk_fma_f32 v[44:45], v[50:51], v[44:45], v[8:9] op_sel_hi:[0,1,1]
	v_pk_fma_f32 v[36:37], v[50:51], v[36:37], v[12:13] op_sel_hi:[0,1,1]
	v_pk_fma_f32 v[42:43], v[50:51], v[42:43], v[2:3] op_sel_hi:[0,1,1]
	v_pk_fma_f32 v[40:41], v[50:51], v[40:41], v[0:1] op_sel_hi:[0,1,1]
	v_pk_fma_f32 v[38:39], v[50:51], v[38:39], v[14:15] op_sel_hi:[0,1,1]
	v_pk_fma_f32 v[32:33], v[50:51], v[32:33], v[4:5] op_sel_hi:[0,1,1]
	v_pk_fma_f32 v[34:35], v[50:51], v[34:35], v[6:7] op_sel_hi:[0,1,1]
	v_pk_mul_f32 v[50:51], v[44:45], s[34:35] op_sel_hi:[1,0]
	v_pk_mul_f32 v[36:37], v[36:37], v[44:45]
	v_pk_mul_f32 v[44:45], v[46:47], s[34:35] op_sel_hi:[1,0]
	v_pk_mul_f32 v[38:39], v[38:39], v[46:47]
	v_exp_f32_e32 v44, v44
	v_exp_f32_e32 v45, v45
	v_pk_mul_f32 v[32:33], v[32:33], v[40:41]
	v_exp_f32_e32 v50, v50
	v_exp_f32_e32 v51, v51
	v_pk_add_f32 v[44:45], v[44:45], 1.0 op_sel_hi:[1,0]
	v_pk_mul_f32 v[34:35], v[34:35], v[42:43]
	v_rcp_f32_e32 v44, v44
	v_rcp_f32_e32 v45, v45
	v_pk_add_f32 v[50:51], v[50:51], 1.0 op_sel_hi:[1,0]
	v_lshl_add_u64 v[48:49], v[48:49], 0, v[160:161]
	v_rcp_f32_e32 v50, v50
	v_pk_mul_f32 v[38:39], v[38:39], v[44:45]
	v_pk_mul_f32 v[44:45], v[40:41], s[34:35] op_sel_hi:[1,0]
	v_rcp_f32_e32 v51, v51
	v_exp_f32_e32 v44, v44
	v_exp_f32_e32 v45, v45
	v_pk_mul_f32 v[36:37], v[36:37], v[50:51]
	v_pk_add_f32 v[44:45], v[44:45], 1.0 op_sel_hi:[1,0]
	s_nop 0
	v_rcp_f32_e32 v44, v44
	v_rcp_f32_e32 v45, v45
	s_nop 0
	v_pk_mul_f32 v[40:41], v[32:33], v[44:45]
	v_pk_mul_f32 v[32:33], v[42:43], s[34:35] op_sel_hi:[1,0]
	s_nop 0
	v_exp_f32_e32 v32, v32
	v_exp_f32_e32 v33, v33
	s_nop 0
	v_pk_add_f32 v[32:33], v[32:33], 1.0 op_sel_hi:[1,0]
	s_nop 0
	v_rcp_f32_e32 v32, v32
	v_rcp_f32_e32 v33, v33
	s_nop 0
	v_pk_mul_f32 v[42:43], v[34:35], v[32:33]
	v_cvt_pk_bf16_f32 v32, v36, v37
	v_cvt_pk_bf16_f32 v33, v38, v39
	v_cvt_pk_bf16_f32 v34, v40, v41
	s_nop 0
	v_cvt_pk_bf16_f32 v35, v42, v43
	global_store_dwordx4 v[48:49], v[32:35], off
	s_nop 1
	v_fmamk_f32 v34, v157, 0x3a800000, v238
	v_rsq_f32_e32 v34, v34
	v_add_u32_e32 v32, 0xb0, v156
	v_mad_i64_i32 v[32:33], s[38:39], v32, s12, v[158:159]
	v_pk_fma_f32 v[8:9], v[34:35], v[28:29], v[8:9] op_sel_hi:[0,1,1]
	v_pk_fma_f32 v[0:1], v[34:35], v[24:25], v[0:1] op_sel_hi:[0,1,1]
	v_pk_fma_f32 v[12:13], v[34:35], v[20:21], v[12:13] op_sel_hi:[0,1,1]
	v_pk_fma_f32 v[4:5], v[34:35], v[16:17], v[4:5] op_sel_hi:[0,1,1]
	v_pk_mul_f32 v[16:17], v[8:9], s[34:35] op_sel_hi:[1,0]
	v_pk_mul_f32 v[8:9], v[12:13], v[8:9]
	v_pk_mul_f32 v[12:13], v[0:1], s[34:35] op_sel_hi:[1,0]
	v_pk_fma_f32 v[10:11], v[34:35], v[30:31], v[10:11] op_sel_hi:[0,1,1]
	v_exp_f32_e32 v12, v12
	v_exp_f32_e32 v13, v13
	v_pk_fma_f32 v[2:3], v[34:35], v[26:27], v[2:3] op_sel_hi:[0,1,1]
	v_pk_fma_f32 v[14:15], v[34:35], v[22:23], v[14:15] op_sel_hi:[0,1,1]
	v_pk_mul_f32 v[0:1], v[4:5], v[0:1]
	v_pk_add_f32 v[12:13], v[12:13], 1.0 op_sel_hi:[1,0]
	v_pk_mul_f32 v[14:15], v[14:15], v[10:11]
	v_rcp_f32_e32 v12, v12
	v_rcp_f32_e32 v13, v13
	v_pk_mul_f32 v[10:11], v[10:11], s[34:35] op_sel_hi:[1,0]
	v_exp_f32_e32 v16, v16
	v_exp_f32_e32 v17, v17
	v_pk_mul_f32 v[4:5], v[0:1], v[12:13]
	v_pk_mul_f32 v[0:1], v[2:3], s[34:35] op_sel_hi:[1,0]
	v_exp_f32_e32 v10, v10
	v_exp_f32_e32 v11, v11
	v_exp_f32_e32 v0, v0
	v_exp_f32_e32 v1, v1
	v_pk_add_f32 v[16:17], v[16:17], 1.0 op_sel_hi:[1,0]
	v_pk_add_f32 v[10:11], v[10:11], 1.0 op_sel_hi:[1,0]
	v_rcp_f32_e32 v16, v16
	v_pk_add_f32 v[0:1], v[0:1], 1.0 op_sel_hi:[1,0]
	v_rcp_f32_e32 v17, v17
	v_rcp_f32_e32 v10, v10
	v_rcp_f32_e32 v11, v11
	v_rcp_f32_e32 v0, v0
	v_rcp_f32_e32 v1, v1
	v_pk_fma_f32 v[6:7], v[34:35], v[18:19], v[6:7] op_sel_hi:[0,1,1]
	v_lshl_add_u64 v[32:33], v[32:33], 0, v[160:161]
	v_pk_mul_f32 v[6:7], v[6:7], v[2:3]
	v_pk_mul_f32 v[8:9], v[8:9], v[16:17]
	v_pk_mul_f32 v[10:11], v[14:15], v[10:11]
	v_pk_mul_f32 v[6:7], v[6:7], v[0:1]
	v_cvt_pk_bf16_f32 v0, v8, v9
	v_cvt_pk_bf16_f32 v1, v10, v11
	v_cvt_pk_bf16_f32 v2, v4, v5
	s_nop 0
	v_cvt_pk_bf16_f32 v3, v6, v7
	global_store_dwordx4 v[32:33], v[0:3], off
	s_cbranch_vccnz .LBB0_265
	s_andn2_b64 vcc, exec, s[8:9]
	s_cbranch_vccnz .LBB0_264
	s_barrier
	s_branch .LBB0_264
